# phase-1 tail state-row copies with 12 chunks in flight per wave instead of 4
# speedup vs baseline: 1.0044x; 1.0044x over previous
; __device__ __forceinline__ void phase0(const Params& p, LAS unsigned char* lds, int wave_s) {
;     ...
;     { const int n4 = MS * 14 * 256;
;       for (int i = blockIdx.x * 512 + tid; i < n4; i += gridDim.x * 512) { const int s = i / (14 * 256), q = i % (14 * 256);
;           ((f32x4*)(p.out + O_POOLS + (size_t)s * 15 * 1024))[q] = ((const f32x4*)(p.in[4] + (size_t)s * 15 * 1024 + 1024))[q]; }
.Lscopy_pool_loop:
	s_cmp_lt_u32 s86, 0x1c00
	s_cbranch_scc0 .Lscopy_pool_done
	s_add_i32 s87, s86, 0x0
	s_cmp_lt_u32 s87, 0x1c00
	s_cbranch_scc0 .Lscopy_pool_ld0
	s_mul_hi_u32 s88, s87, 0x4924925
	s_mul_i32 s89, s88, 0x38
	s_sub_i32 s89, s87, s89
	s_mul_i32 s88, s88, 0xf000
	s_lshl_b32 s89, s89, 10
	s_add_i32 s88, s88, s89
	s_add_i32 s88, s88, 0x1000
	v_add_u32_e32 v2, s88, v1
	global_load_dwordx4 v[16:19], v2, s[60:61]
.Lscopy_pool_ld0:
	s_add_i32 s87, s86, 0x158
	s_cmp_lt_u32 s87, 0x1c00
	s_cbranch_scc0 .Lscopy_pool_ld1
	s_mul_hi_u32 s88, s87, 0x4924925
	s_mul_i32 s89, s88, 0x38
	s_sub_i32 s89, s87, s89
	s_mul_i32 s88, s88, 0xf000
	s_lshl_b32 s89, s89, 10
	s_add_i32 s88, s88, s89
	s_add_i32 s88, s88, 0x1000
	v_add_u32_e32 v3, s88, v1
	global_load_dwordx4 v[20:23], v3, s[60:61]
.Lscopy_pool_ld1:
	s_add_i32 s87, s86, 0x2b0
	s_cmp_lt_u32 s87, 0x1c00
	s_cbranch_scc0 .Lscopy_pool_ld2
	s_mul_hi_u32 s88, s87, 0x4924925
	s_mul_i32 s89, s88, 0x38
	s_sub_i32 s89, s87, s89
	s_mul_i32 s88, s88, 0xf000
	s_lshl_b32 s89, s89, 10
	s_add_i32 s88, s88, s89
	s_add_i32 s88, s88, 0x1000
	v_add_u32_e32 v4, s88, v1
	global_load_dwordx4 v[24:27], v4, s[60:61]
.Lscopy_pool_ld2:
	s_add_i32 s87, s86, 0x408
	s_cmp_lt_u32 s87, 0x1c00
	s_cbranch_scc0 .Lscopy_pool_ld3
	s_mul_hi_u32 s88, s87, 0x4924925
	s_mul_i32 s89, s88, 0x38
	s_sub_i32 s89, s87, s89
	s_mul_i32 s88, s88, 0xf000
	s_lshl_b32 s89, s89, 10
	s_add_i32 s88, s88, s89
	s_add_i32 s88, s88, 0x1000
	v_add_u32_e32 v5, s88, v1
	global_load_dwordx4 v[28:31], v5, s[60:61]
.Lscopy_pool_ld3:
	s_add_i32 s87, s86, 0x560
	s_cmp_lt_u32 s87, 0x1c00
	s_cbranch_scc0 .Lscopy_pool_ld4
	s_mul_hi_u32 s88, s87, 0x4924925
	s_mul_i32 s89, s88, 0x38
	s_sub_i32 s89, s87, s89
	s_mul_i32 s88, s88, 0xf000
	s_lshl_b32 s89, s89, 10
	s_add_i32 s88, s88, s89
	s_add_i32 s88, s88, 0x1000
	v_add_u32_e32 v6, s88, v1
	global_load_dwordx4 v[32:35], v6, s[60:61]
.Lscopy_pool_ld4:
	s_add_i32 s87, s86, 0x6b8
	s_cmp_lt_u32 s87, 0x1c00
	s_cbranch_scc0 .Lscopy_pool_ld5
	s_mul_hi_u32 s88, s87, 0x4924925
	s_mul_i32 s89, s88, 0x38
	s_sub_i32 s89, s87, s89
	s_mul_i32 s88, s88, 0xf000
	s_lshl_b32 s89, s89, 10
	s_add_i32 s88, s88, s89
	s_add_i32 s88, s88, 0x1000
	v_add_u32_e32 v7, s88, v1
	global_load_dwordx4 v[36:39], v7, s[60:61]
.Lscopy_pool_ld5:
	s_add_i32 s87, s86, 0x810
	s_cmp_lt_u32 s87, 0x1c00
	s_cbranch_scc0 .Lscopy_pool_ld6
	s_mul_hi_u32 s88, s87, 0x4924925
	s_mul_i32 s89, s88, 0x38
	s_sub_i32 s89, s87, s89
	s_mul_i32 s88, s88, 0xf000
	s_lshl_b32 s89, s89, 10
	s_add_i32 s88, s88, s89
	s_add_i32 s88, s88, 0x1000
	v_add_u32_e32 v8, s88, v1
	global_load_dwordx4 v[40:43], v8, s[60:61]
.Lscopy_pool_ld6:
	s_add_i32 s87, s86, 0x968
	s_cmp_lt_u32 s87, 0x1c00
	s_cbranch_scc0 .Lscopy_pool_ld7
	s_mul_hi_u32 s88, s87, 0x4924925
	s_mul_i32 s89, s88, 0x38
	s_sub_i32 s89, s87, s89
	s_mul_i32 s88, s88, 0xf000
	s_lshl_b32 s89, s89, 10
	s_add_i32 s88, s88, s89
	s_add_i32 s88, s88, 0x1000
	v_add_u32_e32 v9, s88, v1
	global_load_dwordx4 v[44:47], v9, s[60:61]
.Lscopy_pool_ld7:
	s_add_i32 s87, s86, 0xac0
	s_cmp_lt_u32 s87, 0x1c00
	s_cbranch_scc0 .Lscopy_pool_ld8
	s_mul_hi_u32 s88, s87, 0x4924925
	s_mul_i32 s89, s88, 0x38
	s_sub_i32 s89, s87, s89
	s_mul_i32 s88, s88, 0xf000
	s_lshl_b32 s89, s89, 10
	s_add_i32 s88, s88, s89
	s_add_i32 s88, s88, 0x1000
	v_add_u32_e32 v10, s88, v1
	global_load_dwordx4 v[48:51], v10, s[60:61]
.Lscopy_pool_ld8:
	s_add_i32 s87, s86, 0xc18
	s_cmp_lt_u32 s87, 0x1c00
	s_cbranch_scc0 .Lscopy_pool_ld9
	s_mul_hi_u32 s88, s87, 0x4924925
	s_mul_i32 s89, s88, 0x38
	s_sub_i32 s89, s87, s89
	s_mul_i32 s88, s88, 0xf000
	s_lshl_b32 s89, s89, 10
	s_add_i32 s88, s88, s89
	s_add_i32 s88, s88, 0x1000
	v_add_u32_e32 v11, s88, v1
	global_load_dwordx4 v[52:55], v11, s[60:61]
.Lscopy_pool_ld9:
	s_add_i32 s87, s86, 0xd70
	s_cmp_lt_u32 s87, 0x1c00
	s_cbranch_scc0 .Lscopy_pool_ld10
	s_mul_hi_u32 s88, s87, 0x4924925
	s_mul_i32 s89, s88, 0x38
	s_sub_i32 s89, s87, s89
	s_mul_i32 s88, s88, 0xf000
	s_lshl_b32 s89, s89, 10
	s_add_i32 s88, s88, s89
	s_add_i32 s88, s88, 0x1000
	v_add_u32_e32 v12, s88, v1
	global_load_dwordx4 v[56:59], v12, s[60:61]
.Lscopy_pool_ld10:
	s_add_i32 s87, s86, 0xec8
	s_cmp_lt_u32 s87, 0x1c00
	s_cbranch_scc0 .Lscopy_pool_ld11
	s_mul_hi_u32 s88, s87, 0x4924925
	s_mul_i32 s89, s88, 0x38
	s_sub_i32 s89, s87, s89
	s_mul_i32 s88, s88, 0xf000
	s_lshl_b32 s89, s89, 10
	s_add_i32 s88, s88, s89
	s_add_i32 s88, s88, 0x1000
	v_add_u32_e32 v13, s88, v1
	global_load_dwordx4 v[60:63], v13, s[60:61]
.Lscopy_pool_ld11:
	s_waitcnt vmcnt(0)
	s_add_i32 s87, s86, 0x0
	s_cmp_lt_u32 s87, 0x1c00
	s_cbranch_scc0 .Lscopy_pool_st0
	v_add_u32_e32 v2, 0xfffff000, v2
	global_store_dwordx4 v2, v[16:19], s[92:93]
.Lscopy_pool_st0:
	s_add_i32 s87, s86, 0x158
	s_cmp_lt_u32 s87, 0x1c00
	s_cbranch_scc0 .Lscopy_pool_st1
	v_add_u32_e32 v3, 0xfffff000, v3
	global_store_dwordx4 v3, v[20:23], s[92:93]
.Lscopy_pool_st1:
	s_add_i32 s87, s86, 0x2b0
	s_cmp_lt_u32 s87, 0x1c00
	s_cbranch_scc0 .Lscopy_pool_st2
	v_add_u32_e32 v4, 0xfffff000, v4
	global_store_dwordx4 v4, v[24:27], s[92:93]
.Lscopy_pool_st2:
	s_add_i32 s87, s86, 0x408
	s_cmp_lt_u32 s87, 0x1c00
	s_cbranch_scc0 .Lscopy_pool_st3
	v_add_u32_e32 v5, 0xfffff000, v5
	global_store_dwordx4 v5, v[28:31], s[92:93]
.Lscopy_pool_st3:
	s_add_i32 s87, s86, 0x560
	s_cmp_lt_u32 s87, 0x1c00
	s_cbranch_scc0 .Lscopy_pool_st4
	v_add_u32_e32 v6, 0xfffff000, v6
	global_store_dwordx4 v6, v[32:35], s[92:93]
.Lscopy_pool_st4:
	s_add_i32 s87, s86, 0x6b8
	s_cmp_lt_u32 s87, 0x1c00
	s_cbranch_scc0 .Lscopy_pool_st5
	v_add_u32_e32 v7, 0xfffff000, v7
	global_store_dwordx4 v7, v[36:39], s[92:93]
.Lscopy_pool_st5:
	s_add_i32 s87, s86, 0x810
	s_cmp_lt_u32 s87, 0x1c00
	s_cbranch_scc0 .Lscopy_pool_st6
	v_add_u32_e32 v8, 0xfffff000, v8
	global_store_dwordx4 v8, v[40:43], s[92:93]
.Lscopy_pool_st6:
	s_add_i32 s87, s86, 0x968
	s_cmp_lt_u32 s87, 0x1c00
	s_cbranch_scc0 .Lscopy_pool_st7
	v_add_u32_e32 v9, 0xfffff000, v9
	global_store_dwordx4 v9, v[44:47], s[92:93]
.Lscopy_pool_st7:
	s_add_i32 s87, s86, 0xac0
	s_cmp_lt_u32 s87, 0x1c00
	s_cbranch_scc0 .Lscopy_pool_st8
	v_add_u32_e32 v10, 0xfffff000, v10
	global_store_dwordx4 v10, v[48:51], s[92:93]
.Lscopy_pool_st8:
	s_add_i32 s87, s86, 0xc18
	s_cmp_lt_u32 s87, 0x1c00
	s_cbranch_scc0 .Lscopy_pool_st9
	v_add_u32_e32 v11, 0xfffff000, v11
	global_store_dwordx4 v11, v[52:55], s[92:93]
.Lscopy_pool_st9:
	s_add_i32 s87, s86, 0xd70
	s_cmp_lt_u32 s87, 0x1c00
	s_cbranch_scc0 .Lscopy_pool_st10
	v_add_u32_e32 v12, 0xfffff000, v12
	global_store_dwordx4 v12, v[56:59], s[92:93]
.Lscopy_pool_st10:
	s_add_i32 s87, s86, 0xec8
	s_cmp_lt_u32 s87, 0x1c00
	s_cbranch_scc0 .Lscopy_pool_st11
	v_add_u32_e32 v13, 0xfffff000, v13
	global_store_dwordx4 v13, v[60:63], s[92:93]
.Lscopy_pool_st11:
	s_add_i32 s86, s86, 0x1020
	s_branch .Lscopy_pool_loop

; __device__ __forceinline__ void phase0(const Params& p, LAS unsigned char* lds, int wave_s) {
;     ...
;       const int m4 = MS * 2 * 1536;
;       for (int i = blockIdx.x * 512 + tid; i < m4; i += gridDim.x * 512) { const int s = i / (2 * 1536), q = i % (2 * 1536);
;           ((f32x4*)(p.out + O_CONVS + (size_t)s * 3 * 6144))[q] = ((const f32x4*)(p.in[5] + (size_t)s * 3 * 6144 + 6144))[q]; } }
.Lscopy_conv_loop:
	s_cmp_lt_u32 s86, 0x1800
	s_cbranch_scc0 .Lscopy_conv_done
	s_add_i32 s87, s86, 0x0
	s_cmp_lt_u32 s87, 0x1800
	s_cbranch_scc0 .Lscopy_conv_ld0
	s_mul_hi_u32 s88, s87, 0x5555556
	s_mul_i32 s89, s88, 0x30
	s_sub_i32 s89, s87, s89
	s_mul_i32 s88, s88, 0x12000
	s_lshl_b32 s89, s89, 10
	s_add_i32 s88, s88, s89
	s_add_i32 s88, s88, 0x6000
	v_add_u32_e32 v2, s88, v1
	global_load_dwordx4 v[16:19], v2, s[62:63]
.Lscopy_conv_ld0:
	s_add_i32 s87, s86, 0x158
	s_cmp_lt_u32 s87, 0x1800
	s_cbranch_scc0 .Lscopy_conv_ld1
	s_mul_hi_u32 s88, s87, 0x5555556
	s_mul_i32 s89, s88, 0x30
	s_sub_i32 s89, s87, s89
	s_mul_i32 s88, s88, 0x12000
	s_lshl_b32 s89, s89, 10
	s_add_i32 s88, s88, s89
	s_add_i32 s88, s88, 0x6000
	v_add_u32_e32 v3, s88, v1
	global_load_dwordx4 v[20:23], v3, s[62:63]
.Lscopy_conv_ld1:
	s_add_i32 s87, s86, 0x2b0
	s_cmp_lt_u32 s87, 0x1800
	s_cbranch_scc0 .Lscopy_conv_ld2
	s_mul_hi_u32 s88, s87, 0x5555556
	s_mul_i32 s89, s88, 0x30
	s_sub_i32 s89, s87, s89
	s_mul_i32 s88, s88, 0x12000
	s_lshl_b32 s89, s89, 10
	s_add_i32 s88, s88, s89
	s_add_i32 s88, s88, 0x6000
	v_add_u32_e32 v4, s88, v1
	global_load_dwordx4 v[24:27], v4, s[62:63]
.Lscopy_conv_ld2:
	s_add_i32 s87, s86, 0x408
	s_cmp_lt_u32 s87, 0x1800
	s_cbranch_scc0 .Lscopy_conv_ld3
	s_mul_hi_u32 s88, s87, 0x5555556
	s_mul_i32 s89, s88, 0x30
	s_sub_i32 s89, s87, s89
	s_mul_i32 s88, s88, 0x12000
	s_lshl_b32 s89, s89, 10
	s_add_i32 s88, s88, s89
	s_add_i32 s88, s88, 0x6000
	v_add_u32_e32 v5, s88, v1
	global_load_dwordx4 v[28:31], v5, s[62:63]
.Lscopy_conv_ld3:
	s_add_i32 s87, s86, 0x560
	s_cmp_lt_u32 s87, 0x1800
	s_cbranch_scc0 .Lscopy_conv_ld4
	s_mul_hi_u32 s88, s87, 0x5555556
	s_mul_i32 s89, s88, 0x30
	s_sub_i32 s89, s87, s89
	s_mul_i32 s88, s88, 0x12000
	s_lshl_b32 s89, s89, 10
	s_add_i32 s88, s88, s89
	s_add_i32 s88, s88, 0x6000
	v_add_u32_e32 v6, s88, v1
	global_load_dwordx4 v[32:35], v6, s[62:63]
.Lscopy_conv_ld4:
	s_add_i32 s87, s86, 0x6b8
	s_cmp_lt_u32 s87, 0x1800
	s_cbranch_scc0 .Lscopy_conv_ld5
	s_mul_hi_u32 s88, s87, 0x5555556
	s_mul_i32 s89, s88, 0x30
	s_sub_i32 s89, s87, s89
	s_mul_i32 s88, s88, 0x12000
	s_lshl_b32 s89, s89, 10
	s_add_i32 s88, s88, s89
	s_add_i32 s88, s88, 0x6000
	v_add_u32_e32 v7, s88, v1
	global_load_dwordx4 v[36:39], v7, s[62:63]
.Lscopy_conv_ld5:
	s_add_i32 s87, s86, 0x810
	s_cmp_lt_u32 s87, 0x1800
	s_cbranch_scc0 .Lscopy_conv_ld6
	s_mul_hi_u32 s88, s87, 0x5555556
	s_mul_i32 s89, s88, 0x30
	s_sub_i32 s89, s87, s89
	s_mul_i32 s88, s88, 0x12000
	s_lshl_b32 s89, s89, 10
	s_add_i32 s88, s88, s89
	s_add_i32 s88, s88, 0x6000
	v_add_u32_e32 v8, s88, v1
	global_load_dwordx4 v[40:43], v8, s[62:63]
.Lscopy_conv_ld6:
	s_add_i32 s87, s86, 0x968
	s_cmp_lt_u32 s87, 0x1800
	s_cbranch_scc0 .Lscopy_conv_ld7
	s_mul_hi_u32 s88, s87, 0x5555556
	s_mul_i32 s89, s88, 0x30
	s_sub_i32 s89, s87, s89
	s_mul_i32 s88, s88, 0x12000
	s_lshl_b32 s89, s89, 10
	s_add_i32 s88, s88, s89
	s_add_i32 s88, s88, 0x6000
	v_add_u32_e32 v9, s88, v1
	global_load_dwordx4 v[44:47], v9, s[62:63]
.Lscopy_conv_ld7:
	s_add_i32 s87, s86, 0xac0
	s_cmp_lt_u32 s87, 0x1800
	s_cbranch_scc0 .Lscopy_conv_ld8
	s_mul_hi_u32 s88, s87, 0x5555556
	s_mul_i32 s89, s88, 0x30
	s_sub_i32 s89, s87, s89
	s_mul_i32 s88, s88, 0x12000
	s_lshl_b32 s89, s89, 10
	s_add_i32 s88, s88, s89
	s_add_i32 s88, s88, 0x6000
	v_add_u32_e32 v10, s88, v1
	global_load_dwordx4 v[48:51], v10, s[62:63]
.Lscopy_conv_ld8:
	s_add_i32 s87, s86, 0xc18
	s_cmp_lt_u32 s87, 0x1800
	s_cbranch_scc0 .Lscopy_conv_ld9
	s_mul_hi_u32 s88, s87, 0x5555556
	s_mul_i32 s89, s88, 0x30
	s_sub_i32 s89, s87, s89
	s_mul_i32 s88, s88, 0x12000
	s_lshl_b32 s89, s89, 10
	s_add_i32 s88, s88, s89
	s_add_i32 s88, s88, 0x6000
	v_add_u32_e32 v11, s88, v1
	global_load_dwordx4 v[52:55], v11, s[62:63]
.Lscopy_conv_ld9:
	s_add_i32 s87, s86, 0xd70
	s_cmp_lt_u32 s87, 0x1800
	s_cbranch_scc0 .Lscopy_conv_ld10
	s_mul_hi_u32 s88, s87, 0x5555556
	s_mul_i32 s89, s88, 0x30
	s_sub_i32 s89, s87, s89
	s_mul_i32 s88, s88, 0x12000
	s_lshl_b32 s89, s89, 10
	s_add_i32 s88, s88, s89
	s_add_i32 s88, s88, 0x6000
	v_add_u32_e32 v12, s88, v1
	global_load_dwordx4 v[56:59], v12, s[62:63]
.Lscopy_conv_ld10:
	s_add_i32 s87, s86, 0xec8
	s_cmp_lt_u32 s87, 0x1800
	s_cbranch_scc0 .Lscopy_conv_ld11
	s_mul_hi_u32 s88, s87, 0x5555556
	s_mul_i32 s89, s88, 0x30
	s_sub_i32 s89, s87, s89
	s_mul_i32 s88, s88, 0x12000
	s_lshl_b32 s89, s89, 10
	s_add_i32 s88, s88, s89
	s_add_i32 s88, s88, 0x6000
	v_add_u32_e32 v13, s88, v1
	global_load_dwordx4 v[60:63], v13, s[62:63]
.Lscopy_conv_ld11:
	s_waitcnt vmcnt(0)
	s_add_i32 s87, s86, 0x0
	s_cmp_lt_u32 s87, 0x1800
	s_cbranch_scc0 .Lscopy_conv_st0
	v_add_u32_e32 v2, 0xffffa000, v2
	global_store_dwordx4 v2, v[16:19], s[92:93]
.Lscopy_conv_st0:
	s_add_i32 s87, s86, 0x158
	s_cmp_lt_u32 s87, 0x1800
	s_cbranch_scc0 .Lscopy_conv_st1
	v_add_u32_e32 v3, 0xffffa000, v3
	global_store_dwordx4 v3, v[20:23], s[92:93]
.Lscopy_conv_st1:
	s_add_i32 s87, s86, 0x2b0
	s_cmp_lt_u32 s87, 0x1800
	s_cbranch_scc0 .Lscopy_conv_st2
	v_add_u32_e32 v4, 0xffffa000, v4
	global_store_dwordx4 v4, v[24:27], s[92:93]
.Lscopy_conv_st2:
	s_add_i32 s87, s86, 0x408
	s_cmp_lt_u32 s87, 0x1800
	s_cbranch_scc0 .Lscopy_conv_st3
	v_add_u32_e32 v5, 0xffffa000, v5
	global_store_dwordx4 v5, v[28:31], s[92:93]
.Lscopy_conv_st3:
	s_add_i32 s87, s86, 0x560
	s_cmp_lt_u32 s87, 0x1800
	s_cbranch_scc0 .Lscopy_conv_st4
	v_add_u32_e32 v6, 0xffffa000, v6
	global_store_dwordx4 v6, v[32:35], s[92:93]
.Lscopy_conv_st4:
	s_add_i32 s87, s86, 0x6b8
	s_cmp_lt_u32 s87, 0x1800
	s_cbranch_scc0 .Lscopy_conv_st5
	v_add_u32_e32 v7, 0xffffa000, v7
	global_store_dwordx4 v7, v[36:39], s[92:93]
.Lscopy_conv_st5:
	s_add_i32 s87, s86, 0x810
	s_cmp_lt_u32 s87, 0x1800
	s_cbranch_scc0 .Lscopy_conv_st6
	v_add_u32_e32 v8, 0xffffa000, v8
	global_store_dwordx4 v8, v[40:43], s[92:93]
.Lscopy_conv_st6:
	s_add_i32 s87, s86, 0x968
	s_cmp_lt_u32 s87, 0x1800
	s_cbranch_scc0 .Lscopy_conv_st7
	v_add_u32_e32 v9, 0xffffa000, v9
	global_store_dwordx4 v9, v[44:47], s[92:93]
.Lscopy_conv_st7:
	s_add_i32 s87, s86, 0xac0
	s_cmp_lt_u32 s87, 0x1800
	s_cbranch_scc0 .Lscopy_conv_st8
	v_add_u32_e32 v10, 0xffffa000, v10
	global_store_dwordx4 v10, v[48:51], s[92:93]
.Lscopy_conv_st8:
	s_add_i32 s87, s86, 0xc18
	s_cmp_lt_u32 s87, 0x1800
	s_cbranch_scc0 .Lscopy_conv_st9
	v_add_u32_e32 v11, 0xffffa000, v11
	global_store_dwordx4 v11, v[52:55], s[92:93]
.Lscopy_conv_st9:
	s_add_i32 s87, s86, 0xd70
	s_cmp_lt_u32 s87, 0x1800
	s_cbranch_scc0 .Lscopy_conv_st10
	v_add_u32_e32 v12, 0xffffa000, v12
	global_store_dwordx4 v12, v[56:59], s[92:93]
.Lscopy_conv_st10:
	s_add_i32 s87, s86, 0xec8
	s_cmp_lt_u32 s87, 0x1800
	s_cbranch_scc0 .Lscopy_conv_st11
	v_add_u32_e32 v13, 0xffffa000, v13
	global_store_dwordx4 v13, v[60:63], s[92:93]
